# compress MLP item: load-wait-MFMA loop replaced by 8-deep software pipeline (16 global loads in flight, counted vmcnt)
# baseline (speedup 1.0000x reference)
; #define MFMA32(a, b, c) __builtin_amdgcn_mfma_f32_32x32x16_bf16((a), (b), (c), 0, 0, 0)
; DI void compress_item(const Params& P, unsigned char* smem, int item) {
;     ...
; #pragma unroll 4
;     for (int l = 16 * kh; l < 16 * kh + 16; ++l) {
;         const bf16_t* arow = src + (size_t)(16 * crow_a + l) * LDP; const bf16_t* brow = w1T + (size_t)(32 * nt + l32) * 4096 + l * 128;
; #pragma unroll
;         for (int ks = 0; ks < 8; ++ks) { const bf16x8 a = *(const bf16x8*)(arow + 16 * ks + 8 * hh), bb = *(const bf16x8*)(brow + 16 * ks + 8 * hh); acc = MFMA32(a, bb, acc); }
;     }
.LBB0_255:
	v_lshl_add_u64 v[132:133], v[16:17], 0, v[64:65]
	v_lshl_add_u64 v[140:141], v[18:19], 0, v[64:65]
	s_mov_b64 s[0:1], 0x7600
	v_lshl_add_u64 v[134:135], v[132:133], 0, s[0:1]
	s_mov_b64 s[0:1], 0xec00
	v_lshl_add_u64 v[136:137], v[132:133], 0, s[0:1]
	s_mov_b64 s[0:1], 0x16200
	v_lshl_add_u64 v[138:139], v[132:133], 0, s[0:1]
	s_add_i32 s70, s70, -4
	global_load_dwordx4 v[68:71], v[132:133], off
	global_load_dwordx4 v[100:103], v[140:141], off
	global_load_dwordx4 v[72:75], v[132:133], off offset:32
	global_load_dwordx4 v[104:107], v[140:141], off offset:32
	global_load_dwordx4 v[76:79], v[132:133], off offset:64
	global_load_dwordx4 v[108:111], v[140:141], off offset:64
	global_load_dwordx4 v[80:83], v[132:133], off offset:96
	global_load_dwordx4 v[112:115], v[140:141], off offset:96
	global_load_dwordx4 v[84:87], v[132:133], off offset:128
	global_load_dwordx4 v[116:119], v[140:141], off offset:128
	global_load_dwordx4 v[88:91], v[132:133], off offset:160
	global_load_dwordx4 v[120:123], v[140:141], off offset:160
	global_load_dwordx4 v[92:95], v[132:133], off offset:192
	global_load_dwordx4 v[124:127], v[140:141], off offset:192
	global_load_dwordx4 v[96:99], v[132:133], off offset:224
	global_load_dwordx4 v[128:131], v[140:141], off offset:224
	s_waitcnt vmcnt(14)
	v_mfma_f32_32x32x16_bf16 v[0:15], v[68:71], v[100:103], v[0:15]
	global_load_dwordx4 v[68:71], v[134:135], off
	global_load_dwordx4 v[100:103], v[140:141], off offset:256
	s_waitcnt vmcnt(14)
	v_mfma_f32_32x32x16_bf16 v[0:15], v[72:75], v[104:107], v[0:15]
	global_load_dwordx4 v[72:75], v[134:135], off offset:32
	global_load_dwordx4 v[104:107], v[140:141], off offset:288
	s_waitcnt vmcnt(14)
	v_mfma_f32_32x32x16_bf16 v[0:15], v[76:79], v[108:111], v[0:15]
	global_load_dwordx4 v[76:79], v[134:135], off offset:64
	global_load_dwordx4 v[108:111], v[140:141], off offset:320
	s_waitcnt vmcnt(14)
	v_mfma_f32_32x32x16_bf16 v[0:15], v[80:83], v[112:115], v[0:15]
	global_load_dwordx4 v[80:83], v[134:135], off offset:96
	global_load_dwordx4 v[112:115], v[140:141], off offset:352
	s_waitcnt vmcnt(14)
	v_mfma_f32_32x32x16_bf16 v[0:15], v[84:87], v[116:119], v[0:15]
	global_load_dwordx4 v[84:87], v[134:135], off offset:128
	global_load_dwordx4 v[116:119], v[140:141], off offset:384
	s_waitcnt vmcnt(14)
	v_mfma_f32_32x32x16_bf16 v[0:15], v[88:91], v[120:123], v[0:15]
	global_load_dwordx4 v[88:91], v[134:135], off offset:160
	global_load_dwordx4 v[120:123], v[140:141], off offset:416
	s_waitcnt vmcnt(14)
	v_mfma_f32_32x32x16_bf16 v[0:15], v[92:95], v[124:127], v[0:15]
	global_load_dwordx4 v[92:95], v[134:135], off offset:192
	global_load_dwordx4 v[124:127], v[140:141], off offset:448
	s_waitcnt vmcnt(14)
	v_mfma_f32_32x32x16_bf16 v[0:15], v[96:99], v[128:131], v[0:15]
	global_load_dwordx4 v[96:99], v[134:135], off offset:224
	global_load_dwordx4 v[128:131], v[140:141], off offset:480
	s_waitcnt vmcnt(14)
	v_mfma_f32_32x32x16_bf16 v[0:15], v[68:71], v[100:103], v[0:15]
	global_load_dwordx4 v[68:71], v[136:137], off
	global_load_dwordx4 v[100:103], v[140:141], off offset:512
	s_waitcnt vmcnt(14)
	v_mfma_f32_32x32x16_bf16 v[0:15], v[72:75], v[104:107], v[0:15]
	global_load_dwordx4 v[72:75], v[136:137], off offset:32
	global_load_dwordx4 v[104:107], v[140:141], off offset:544
	s_waitcnt vmcnt(14)
	v_mfma_f32_32x32x16_bf16 v[0:15], v[76:79], v[108:111], v[0:15]
	global_load_dwordx4 v[76:79], v[136:137], off offset:64
	global_load_dwordx4 v[108:111], v[140:141], off offset:576
	s_waitcnt vmcnt(14)
	v_mfma_f32_32x32x16_bf16 v[0:15], v[80:83], v[112:115], v[0:15]
	global_load_dwordx4 v[80:83], v[136:137], off offset:96
	global_load_dwordx4 v[112:115], v[140:141], off offset:608
	s_waitcnt vmcnt(14)
	v_mfma_f32_32x32x16_bf16 v[0:15], v[84:87], v[116:119], v[0:15]
	global_load_dwordx4 v[84:87], v[136:137], off offset:128
	global_load_dwordx4 v[116:119], v[140:141], off offset:640
	s_waitcnt vmcnt(14)
	v_mfma_f32_32x32x16_bf16 v[0:15], v[88:91], v[120:123], v[0:15]
	global_load_dwordx4 v[88:91], v[136:137], off offset:160
	global_load_dwordx4 v[120:123], v[140:141], off offset:672
	s_waitcnt vmcnt(14)
	v_mfma_f32_32x32x16_bf16 v[0:15], v[92:95], v[124:127], v[0:15]
	global_load_dwordx4 v[92:95], v[136:137], off offset:192
	global_load_dwordx4 v[124:127], v[140:141], off offset:704
	s_waitcnt vmcnt(14)
	v_mfma_f32_32x32x16_bf16 v[0:15], v[96:99], v[128:131], v[0:15]
	global_load_dwordx4 v[96:99], v[136:137], off offset:224
	global_load_dwordx4 v[128:131], v[140:141], off offset:736
	s_waitcnt vmcnt(14)
	v_mfma_f32_32x32x16_bf16 v[0:15], v[68:71], v[100:103], v[0:15]
	global_load_dwordx4 v[68:71], v[138:139], off
	global_load_dwordx4 v[100:103], v[140:141], off offset:768
	s_waitcnt vmcnt(14)
	v_mfma_f32_32x32x16_bf16 v[0:15], v[72:75], v[104:107], v[0:15]
	global_load_dwordx4 v[72:75], v[138:139], off offset:32
	global_load_dwordx4 v[104:107], v[140:141], off offset:800
	s_waitcnt vmcnt(14)
	v_mfma_f32_32x32x16_bf16 v[0:15], v[76:79], v[108:111], v[0:15]
	global_load_dwordx4 v[76:79], v[138:139], off offset:64
	global_load_dwordx4 v[108:111], v[140:141], off offset:832
	s_waitcnt vmcnt(14)
	v_mfma_f32_32x32x16_bf16 v[0:15], v[80:83], v[112:115], v[0:15]
	global_load_dwordx4 v[80:83], v[138:139], off offset:96
	global_load_dwordx4 v[112:115], v[140:141], off offset:864
	s_waitcnt vmcnt(14)
	v_mfma_f32_32x32x16_bf16 v[0:15], v[84:87], v[116:119], v[0:15]
	global_load_dwordx4 v[84:87], v[138:139], off offset:128
	global_load_dwordx4 v[116:119], v[140:141], off offset:896
	s_waitcnt vmcnt(14)
	v_mfma_f32_32x32x16_bf16 v[0:15], v[88:91], v[120:123], v[0:15]
	global_load_dwordx4 v[88:91], v[138:139], off offset:160
	global_load_dwordx4 v[120:123], v[140:141], off offset:928
	s_waitcnt vmcnt(14)
	v_mfma_f32_32x32x16_bf16 v[0:15], v[92:95], v[124:127], v[0:15]
	global_load_dwordx4 v[92:95], v[138:139], off offset:192
	global_load_dwordx4 v[124:127], v[140:141], off offset:960
	s_waitcnt vmcnt(14)
	v_mfma_f32_32x32x16_bf16 v[0:15], v[96:99], v[128:131], v[0:15]
	global_load_dwordx4 v[96:99], v[138:139], off offset:224
	global_load_dwordx4 v[128:131], v[140:141], off offset:992
	s_waitcnt vmcnt(14)
	v_mfma_f32_32x32x16_bf16 v[0:15], v[68:71], v[100:103], v[0:15]
	s_waitcnt vmcnt(12)
	v_mfma_f32_32x32x16_bf16 v[0:15], v[72:75], v[104:107], v[0:15]
	s_waitcnt vmcnt(10)
	v_mfma_f32_32x32x16_bf16 v[0:15], v[76:79], v[108:111], v[0:15]
	s_waitcnt vmcnt(8)
	v_mfma_f32_32x32x16_bf16 v[0:15], v[80:83], v[112:115], v[0:15]
	s_waitcnt vmcnt(6)
	v_mfma_f32_32x32x16_bf16 v[0:15], v[84:87], v[116:119], v[0:15]
	s_waitcnt vmcnt(4)
	v_mfma_f32_32x32x16_bf16 v[0:15], v[88:91], v[120:123], v[0:15]
	s_waitcnt vmcnt(2)
	v_mfma_f32_32x32x16_bf16 v[0:15], v[92:95], v[124:127], v[0:15]
	s_waitcnt vmcnt(0)
	v_mfma_f32_32x32x16_bf16 v[0:15], v[96:99], v[128:131], v[0:15]
	s_mov_b64 s[0:1], 0x1d800
	v_lshl_add_u64 v[16:17], v[16:17], 0, s[0:1]
	s_mov_b64 s[0:1], 0x400
	v_lshl_add_u64 v[18:19], v[18:19], 0, s[0:1]
	s_cmp_eq_u32 s70, 0
	s_cbranch_scc0 .LBB0_255
; DI void compress_item(const Params& P, unsigned char* smem, int item) {
;     ...
;     __syncthreads();
;     if (kh == 1) {
; #pragma unroll
;         for (int i = 0; i < 16; ++i) red[(nt * 64 + lane) * 16 + i] = acc[i]; }
	v_cmp_eq_u32_e32 vcc, 1, v28
	s_barrier
	s_and_saveexec_b64 s[70:71], vcc
	s_cbranch_execz .LBB0_258
	v_lshlrev_b32_e32 v16, 6, v24
	v_and_b32_e32 v16, 0x3fc0, v16
	v_add_u32_e32 v16, 0, v16
	s_nop 3
	ds_write_b128 v16, v[0:3]
	ds_write_b128 v16, v[4:7] offset:16
	ds_write_b128 v16, v[8:11] offset:32
	ds_write_b128 v16, v[12:15] offset:48
